# speedup vs baseline: 1.0337x; 1.0109x over previous
; #define PG8_STAGE(bufoff, gbase, voff) do { _Pragma("unroll") for (int _i = 0; _i < 2; ++_i) \
;         __builtin_amdgcn_global_load_lds((const unsigned*)((const char*)(gbase) + (voff)[_i]), (LAS unsigned*)(lds + (bufoff) + ldsw + _i * 8192), 16, 0, 0); } while (0)
; template <class Epi, class Pre, bool AG = false>
; __device__ __forceinline__ void gemm_phase(LAS unsigned char* lds, const Gemm g, const StaticOrder& S, const Epi& E, const Pre& P) {
;     int tid_ = threadIdx.x; asm volatile("" : "+v"(tid_));
;     const int tid = tid_, wid = __builtin_amdgcn_readfirstlane(tid >> 6), lane = tid & 63, wr = wid >> 2, wc = wid & 3, fr = lane & 15, fq = lane >> 4;
;     const int K = g.K, nt = K / BK;
;     unsigned voffA[2], voffB[2];
; #pragma unroll
;     for (int i = 0; i < 2; ++i) { int R, C; stage_rc(tid * 16 + i * 8192, R, C); const int Rb = Epi::PERM ? ((R & ~31) + perm32(R & 31)) : R;
;         voffA[i] = AG ? (unsigned)((C >> 4) * g.M * 16 + R * 16 + (C & 15)) * 2u : (unsigned)(R * K + C) * 2u; voffB[i] = (unsigned)(Rb * K + C) * 2u; }
;     const size_t kstep = (size_t)(BK * 2), kstepA = AG ? (size_t)(BK / 16) * g.M * 32 : kstep;
;     const size_t hstep = (size_t)HALF * K * 2, hstepA = AG ? (size_t)HALF * 32 : hstep;
;     const size_t tstep = 2 * hstep, tstepA = 2 * hstepA;
;     const unsigned ldsw = (unsigned)wid * 1024u;
;     const int aoff = lds_byte(wr * 64 + fr, fq * 8), boff = lds_byte(wc * 32 + fr, fq * 8);
;     ...
;     Unit cur, nxt; int ui = 0;
;     if (!S.next(0, cur)) return;
;     f32x4 acc[2][2][4][2];
; #pragma unroll
;     for (int a = 0; a < 2; ++a)
; #pragma unroll
;         for (int b = 0; b < 2; ++b)
; #pragma unroll
;             for (int m = 0; m < 4; ++m)
; #pragma unroll
;                 for (int n = 0; n < 2; ++n) acc[a][b][m][n] = (f32x4){0.f, 0.f, 0.f, 0.f};
;     bf16x8 At[4][2], B0[2][2], B1[2][2];
;     const char* cA = (const char*)g.A + (size_t)cur.pm * tstepA; const char* cB = (const char*)g.Bt + (size_t)cur.pn * tstep;
;     PG8_STAGE(PG8_SB(0, 0), cB, voffB); PG8_STAGE(PG8_SB(0, 1), cB + hstep, voffB); PG8_STAGE(PG8_SA(0, 0), cA, voffA); PG8_STAGE(PG8_SA(0, 1), cA + hstepA, voffA);
;     P(S);
.LBB0_197:
	v_readlane_b32 s6, v254, 16
	s_mov_b64 s[0:1], s[40:41]
	v_mov_b32_e32 v15, v234
	v_readlane_b32 s7, v254, 17
	s_and_b64 vcc, exec, s[6:7]
	v_readfirstlane_b32 s16, v15
	s_cbranch_vccz .LBB0_219
	v_lshlrev_b32_e32 v0, 4, v15
	v_add_u32_e32 v2, 0x2000, v0
	v_ashrrev_i32_e32 v3, 31, v2
	v_lshrrev_b32_e32 v3, 22, v3
	s_load_dwordx2 s[8:9], s[0:1], 0x100
	v_add_u32_e32 v3, v2, v3
	v_ashrrev_i32_e32 v10, 10, v3
	v_mul_i32_i24_e32 v3, 0x400, v10
	s_and_b64 s[0:1], s[94:95], exec
	v_sub_u32_e32 v2, v2, v3
	s_mov_b32 s0, 0xe910000
	s_mov_b32 s6, 0x12910000
	v_readlane_b32 s7, v254, 20
	v_lshrrev_b32_e32 v3, 4, v2
	s_cselect_b32 s0, s0, 0xc910000
	s_cselect_b32 s1, 0, 0x1700000
	s_cselect_b32 s6, s6, 0x12a10000
	s_waitcnt lgkmcnt(0)
	s_add_u32 s7, s8, s7
	v_bitop3_b32 v2, v3, v2, 32 bitop3:0x6c
	s_addc_u32 s10, s9, 0
	v_ashrrev_i32_e32 v3, 31, v2
	s_add_u32 s20, s8, s0
	v_lshrrev_b32_e32 v3, 26, v3
	s_addc_u32 s24, s9, 0
	v_add_u32_e32 v3, v2, v3
	v_lshlrev_b32_e32 v4, 3, v10
	s_add_u32 s25, s7, s1
	v_ashrrev_i32_e32 v11, 6, v3
	v_and_b32_e32 v4, -16, v4
	s_addc_u32 s30, s10, 0
	v_add_u32_e32 v4, v11, v4
	s_add_u32 s0, s8, s6
	v_and_b32_e32 v5, 3, v11
	s_mov_b32 s6, 0x1fffe0
	v_lshrrev_b32_e32 v6, 2, v4
	v_lshlrev_b32_e32 v7, 1, v4
	v_and_b32_e32 v3, 0xc0, v3
	v_and_or_b32 v5, v4, s6, v5
	v_and_b32_e32 v6, 4, v6
	v_and_b32_e32 v7, 24, v7
	v_sub_u32_e32 v2, v2, v3
	v_mov_b32_e32 v8, 1
	v_or3_b32 v5, v5, v6, v7
	v_lshlrev_b32_e32 v6, 5, v10
	v_ashrrev_i16_sdwa v2, v8, sext(v2) dst_sel:DWORD dst_unused:UNUSED_PAD src0_sel:DWORD src1_sel:BYTE_0
	v_and_b32_e32 v6, 32, v6
	v_bfe_i32 v12, v2, 0, 16
	v_add_lshl_u32 v2, v6, v12, 1
	v_lshl_add_u32 v130, v5, 11, v2
	v_lshl_add_u32 v132, v4, 11, v2
	v_bfe_i32 v2, v15, 27, 1
	v_lshrrev_b32_e32 v2, 22, v2
	v_add_u32_e32 v2, v0, v2
	v_and_b32_e32 v2, 0xfffffc00, v2
	v_sub_u32_e32 v0, v0, v2
	v_lshrrev_b32_e32 v2, 4, v0
	v_ashrrev_i32_e32 v4, 31, v15
	v_bitop3_b32 v2, v2, v0, 32 bitop3:0x6c
	v_lshrrev_b32_e32 v4, 26, v4
	v_ashrrev_i32_e32 v0, 31, v2
	v_add_u32_e32 v4, v15, v4
	v_lshrrev_b32_e32 v0, 26, v0
	v_ashrrev_i32_e32 v13, 6, v4
	v_add_u32_e32 v3, v2, v0
	v_lshlrev_b32_e32 v4, 3, v13
	v_ashrrev_i32_e32 v0, 6, v3
	v_and_b32_e32 v4, -16, v4
	v_add_u32_e32 v4, v0, v4
	v_and_b32_e32 v5, 3, v0
	v_lshrrev_b32_e32 v6, 2, v4
	v_lshlrev_b32_e32 v7, 1, v4
	v_and_b32_e32 v3, 0xc0, v3
	s_addc_u32 s1, s9, 0
	s_ashr_i32 s17, s16, 6
	v_and_or_b32 v5, v4, s6, v5
	v_and_b32_e32 v6, 4, v6
	v_and_b32_e32 v7, 24, v7
	v_sub_u32_e32 v2, v2, v3
	s_lshl_b32 s31, s17, 10
	v_or3_b32 v5, v5, v6, v7
	v_lshlrev_b32_e32 v6, 5, v13
	v_ashrrev_i16_sdwa v2, v8, sext(v2) dst_sel:DWORD dst_unused:UNUSED_PAD src0_sel:DWORD src1_sel:BYTE_0
	v_readlane_b32 s6, v254, 44
	v_and_b32_e32 v6, 32, v6
	v_bfe_i32 v14, v2, 0, 16
	v_readlane_b32 s7, v254, 45
	s_add_u32 s46, s25, s6
	v_add_lshl_u32 v2, v6, v14, 1
	s_addc_u32 s47, s30, s7
	s_add_i32 s38, s31, 0
	v_lshl_add_u32 v134, v5, 11, v2
	s_add_i32 m0, s38, 0x10000
	v_lshl_add_u32 v136, v4, 11, v2
	global_load_lds_dwordx4 v134, s[46:47]
	s_add_i32 m0, s38, 0x12000
	s_add_u32 s6, s46, 0x40000
	global_load_lds_dwordx4 v130, s[46:47]
	s_addc_u32 s7, s47, 0
	s_add_i32 m0, s38, 0x14000
	v_mov_b32_e32 v135, v1
	global_load_lds_dwordx4 v134, s[6:7]
	s_add_i32 m0, s38, 0x16000
	v_mov_b32_e32 v131, v1
	global_load_lds_dwordx4 v130, s[6:7]
	v_readlane_b32 s6, v254, 42
	v_readlane_b32 s7, v254, 43
	s_add_u32 s44, s20, s6
	s_addc_u32 s45, s24, s7
	s_add_i32 s48, s38, 0x2000
	s_mov_b32 m0, s38
	s_add_u32 s6, s44, 0x40000
	global_load_lds_dwordx4 v136, s[44:45]
	s_mov_b32 m0, s48
	s_addc_u32 s7, s45, 0
	s_add_i32 s49, s38, 0x4000
	global_load_lds_dwordx4 v132, s[44:45]
	s_mov_b32 m0, s49
	s_add_i32 s53, s38, 0x6000
	global_load_lds_dwordx4 v136, s[6:7]
	s_mov_b32 m0, s53
	v_mov_b32_e32 v137, v1
	global_load_lds_dwordx4 v132, s[6:7]
	v_mov_b32_e32 v133, v1
	v_mov_b32_e32 v16, v234
	s_movk_i32 s6, 0x100
	v_readlane_b32 s10, v254, 12
	v_lshl_add_u64 v[8:9], s[46:47], 0, v[134:135]
	v_lshl_add_u64 v[6:7], s[46:47], 0, v[130:131]
	v_lshl_add_u64 v[4:5], s[44:45], 0, v[136:137]
	v_lshl_add_u64 v[2:3], s[44:45], 0, v[132:133]
	s_movk_i32 s26, 0xc400
	v_cmp_gt_i32_e64 s[6:7], s6, v16
	v_lshl_add_u32 v17, v16, 2, s10
	s_mov_b64 s[10:11], s[2:3]
	s_cmp_eq_u32 s18, 0x100
	s_cbranch_scc1 .Lpr_gu_begin
	s_branch .LBB0_201

; #define LAS __attribute__((address_space(3)))
;     __host__ __device__ bool next(int i, Unit& u) const {
;         const long L = (long)i * G + c; if (L >= nwg) return false;
;         int wgid = (int)L; { const int q = nwg / NXCD, r = nwg % NXCD, xcd = wgid % NXCD, off = wgid / NXCD; wgid = (xcd < r ? xcd * (q + 1) : r * (q + 1) + (xcd - r) * q) + off; }
;         const int nig = WGM * nN, gid = wgid / nig, fm = gid * WGM, gsz = (nM - fm) < WGM ? (nM - fm) : WGM;
;         u.pm = fm + ((wgid % nig) % gsz); u.pn = (wgid % nig) / gsz; return true;
; template <int NS> __device__ __forceinline__ void prep_rstd(LAS unsigned char* lds, const float* part, const pg8::StaticOrder& S, float inv_n) {
;     LAS float* t = (LAS float*)(lds + LDS_RS_OFF);
;     int tid = threadIdx.x; asm volatile("" : "+v"(tid));
;     pg8::Unit u;
;     for (int i = 0; i < RS_MAX_UNITS && S.next(i, u); ++i) {
;         if (tid < 256) {
;             const f32x4* p = (const f32x4*)(part + (size_t)(u.pm * 256 + tid) * NS);
;             f32x4 a = p[0], b = p[1];
;             float s = ((a.x + a.y) + (a.z + a.w)) + ((b.x + b.y) + (b.z + b.w));
;             if (NS == 16) { a = p[2]; b = p[3]; s += ((a.x + a.y) + (a.z + a.w)) + ((b.x + b.y) + (b.z + b.w)); }
;             t[i * 256 + tid] = rsqrtf(s * inv_n + EPS);
;         }
;     }
.Lpr_gu_begin:
	s_and_saveexec_b64 s[12:13], s[6:7]
	s_cbranch_execz .Lpr_gu_done
	v_lshlrev_b32_e32 v116, 6, v16
	s_mov_b32 s26, 0
	s_mov_b32 s10, s2
	s_cmp_gt_u32 s10, 0x57f
	s_cbranch_scc1 .Lpr_gu_wait
	s_and_b32 s27, s10, 7
	s_mul_i32 s27, s27, 0xb0
	s_lshr_b32 s28, s10, 3
	s_add_i32 s27, s27, s28
	s_mul_hi_u32 s28, s27, 0x2e8ba2e9
	s_lshr_b32 s28, s28, 4
	s_lshl_b32 s28, s28, 2
	s_and_b32 s27, s27, 3
	s_or_b32 s27, s27, s28
	s_lshl_b32 s27, s27, 14
	s_add_u32 s28, s0, s27
	s_addc_u32 s29, s1, 0
	global_load_dwordx4 v[18:21], v116, s[28:29]
	global_load_dwordx4 v[22:25], v116, s[28:29] offset:16
	global_load_dwordx4 v[26:29], v116, s[28:29] offset:32
	global_load_dwordx4 v[30:33], v116, s[28:29] offset:48
	s_add_i32 s26, s26, 1
	s_add_i32 s10, s10, s18
	s_cmp_gt_u32 s10, 0x57f
	s_cbranch_scc1 .Lpr_gu_wait
	s_and_b32 s27, s10, 7
	s_mul_i32 s27, s27, 0xb0
	s_lshr_b32 s28, s10, 3
	s_add_i32 s27, s27, s28
	s_mul_hi_u32 s28, s27, 0x2e8ba2e9
	s_lshr_b32 s28, s28, 4
	s_lshl_b32 s28, s28, 2
	s_and_b32 s27, s27, 3
	s_or_b32 s27, s27, s28
	s_lshl_b32 s27, s27, 14
	s_add_u32 s28, s0, s27
	s_addc_u32 s29, s1, 0
	global_load_dwordx4 v[36:39], v116, s[28:29]
	global_load_dwordx4 v[40:43], v116, s[28:29] offset:16
	global_load_dwordx4 v[44:47], v116, s[28:29] offset:32
	global_load_dwordx4 v[48:51], v116, s[28:29] offset:48
	s_add_i32 s26, s26, 1
	s_add_i32 s10, s10, s18
	s_cmp_gt_u32 s10, 0x57f
	s_cbranch_scc1 .Lpr_gu_wait
	s_and_b32 s27, s10, 7
	s_mul_i32 s27, s27, 0xb0
	s_lshr_b32 s28, s10, 3
	s_add_i32 s27, s27, s28
	s_mul_hi_u32 s28, s27, 0x2e8ba2e9
	s_lshr_b32 s28, s28, 4
	s_lshl_b32 s28, s28, 2
	s_and_b32 s27, s27, 3
	s_or_b32 s27, s27, s28
	s_lshl_b32 s27, s27, 14
	s_add_u32 s28, s0, s27
	s_addc_u32 s29, s1, 0
	global_load_dwordx4 v[52:55], v116, s[28:29]
	global_load_dwordx4 v[56:59], v116, s[28:29] offset:16
	global_load_dwordx4 v[60:63], v116, s[28:29] offset:32
	global_load_dwordx4 v[64:67], v116, s[28:29] offset:48
	s_add_i32 s26, s26, 1
	s_add_i32 s10, s10, s18
	s_cmp_gt_u32 s10, 0x57f
	s_cbranch_scc1 .Lpr_gu_wait
	s_and_b32 s27, s10, 7
	s_mul_i32 s27, s27, 0xb0
	s_lshr_b32 s28, s10, 3
	s_add_i32 s27, s27, s28
	s_mul_hi_u32 s28, s27, 0x2e8ba2e9
	s_lshr_b32 s28, s28, 4
	s_lshl_b32 s28, s28, 2
	s_and_b32 s27, s27, 3
	s_or_b32 s27, s27, s28
	s_lshl_b32 s27, s27, 14
	s_add_u32 s28, s0, s27
	s_addc_u32 s29, s1, 0
	global_load_dwordx4 v[68:71], v116, s[28:29]
	global_load_dwordx4 v[72:75], v116, s[28:29] offset:16
	global_load_dwordx4 v[76:79], v116, s[28:29] offset:32
	global_load_dwordx4 v[80:83], v116, s[28:29] offset:48
	s_add_i32 s26, s26, 1
	s_add_i32 s10, s10, s18
	s_cmp_gt_u32 s10, 0x57f
	s_cbranch_scc1 .Lpr_gu_wait
	s_and_b32 s27, s10, 7
	s_mul_i32 s27, s27, 0xb0
	s_lshr_b32 s28, s10, 3
	s_add_i32 s27, s27, s28
	s_mul_hi_u32 s28, s27, 0x2e8ba2e9
	s_lshr_b32 s28, s28, 4
	s_lshl_b32 s28, s28, 2
	s_and_b32 s27, s27, 3
	s_or_b32 s27, s27, s28
	s_lshl_b32 s27, s27, 14
	s_add_u32 s28, s0, s27
	s_addc_u32 s29, s1, 0
	global_load_dwordx4 v[84:87], v116, s[28:29]
	global_load_dwordx4 v[88:91], v116, s[28:29] offset:16
	global_load_dwordx4 v[92:95], v116, s[28:29] offset:32
	global_load_dwordx4 v[96:99], v116, s[28:29] offset:48
	s_add_i32 s26, s26, 1
	s_add_i32 s10, s10, s18
	s_cmp_gt_u32 s10, 0x57f
	s_cbranch_scc1 .Lpr_gu_wait
	s_and_b32 s27, s10, 7
	s_mul_i32 s27, s27, 0xb0
	s_lshr_b32 s28, s10, 3
	s_add_i32 s27, s27, s28
	s_mul_hi_u32 s28, s27, 0x2e8ba2e9
	s_lshr_b32 s28, s28, 4
	s_lshl_b32 s28, s28, 2
	s_and_b32 s27, s27, 3
	s_or_b32 s27, s27, s28
	s_lshl_b32 s27, s27, 14
	s_add_u32 s28, s0, s27
	s_addc_u32 s29, s1, 0
	global_load_dwordx4 v[100:103], v116, s[28:29]
	global_load_dwordx4 v[104:107], v116, s[28:29] offset:16
	global_load_dwordx4 v[108:111], v116, s[28:29] offset:32
	global_load_dwordx4 v[112:115], v116, s[28:29] offset:48
	s_add_i32 s26, s26, 1
	s_add_i32 s10, s10, s18
; template <int NS> __device__ __forceinline__ void prep_rstd(LAS unsigned char* lds, const float* part, const pg8::StaticOrder& S, float inv_n) {
;     ...
;     for (int i = 0; i < RS_MAX_UNITS && S.next(i, u); ++i) {
;         if (tid < 256) {
;             const f32x4* p = (const f32x4*)(part + (size_t)(u.pm * 256 + tid) * NS);
;             f32x4 a = p[0], b = p[1];
;             float s = ((a.x + a.y) + (a.z + a.w)) + ((b.x + b.y) + (b.z + b.w));
;             if (NS == 16) { a = p[2]; b = p[3]; s += ((a.x + a.y) + (a.z + a.w)) + ((b.x + b.y) + (b.z + b.w)); }
;             t[i * 256 + tid] = rsqrtf(s * inv_n + EPS);
;         }
;     }
;     __syncthreads();
.Lpr_gu_wait:
	s_waitcnt vmcnt(0)
	s_cmp_lt_u32 s26, 1
	s_cbranch_scc1 .Lpr_gu_done
	v_add_f32_e32 v18, v18, v19
	v_add_f32_e32 v20, v20, v21
	v_add_f32_e32 v18, v18, v20
	v_add_f32_e32 v22, v22, v23
	v_add_f32_e32 v24, v24, v25
	v_add_f32_e32 v22, v22, v24
	v_add_f32_e32 v26, v26, v27
	v_add_f32_e32 v28, v28, v29
	v_add_f32_e32 v26, v26, v28
	v_add_f32_e32 v30, v30, v31
	v_add_f32_e32 v32, v32, v33
	v_add_f32_e32 v30, v30, v32
	v_add_f32_e32 v18, v18, v22
	v_add_f32_e32 v26, v26, v30
	v_add_f32_e32 v118, v18, v26
	v_fmamk_f32 v118, v118, 0x3a800000, v230
	v_mul_f32_e32 v124, 0x4b800000, v118
	v_cmp_gt_f32_e32 vcc, s35, v118
	s_nop 1
	v_cndmask_b32_e32 v118, v118, v124, vcc
	v_rsq_f32_e32 v118, v118
	s_nop 0
	v_mul_f32_e32 v124, 0x45800000, v118
	v_cndmask_b32_e32 v118, v118, v124, vcc
	ds_write_b32 v17, v118
	s_cmp_lt_u32 s26, 2
	s_cbranch_scc1 .Lpr_gu_done
	v_add_f32_e32 v36, v36, v37
	v_add_f32_e32 v38, v38, v39
	v_add_f32_e32 v36, v36, v38
	v_add_f32_e32 v40, v40, v41
	v_add_f32_e32 v42, v42, v43
	v_add_f32_e32 v40, v40, v42
	v_add_f32_e32 v44, v44, v45
	v_add_f32_e32 v46, v46, v47
	v_add_f32_e32 v44, v44, v46
	v_add_f32_e32 v48, v48, v49
	v_add_f32_e32 v50, v50, v51
	v_add_f32_e32 v48, v48, v50
	v_add_f32_e32 v36, v36, v40
	v_add_f32_e32 v44, v44, v48
	v_add_f32_e32 v119, v36, v44
	v_fmamk_f32 v119, v119, 0x3a800000, v230
	v_mul_f32_e32 v125, 0x4b800000, v119
	v_cmp_gt_f32_e32 vcc, s35, v119
	s_nop 1
	v_cndmask_b32_e32 v119, v119, v125, vcc
	v_rsq_f32_e32 v119, v119
	s_nop 0
	v_mul_f32_e32 v125, 0x45800000, v119
	v_cndmask_b32_e32 v119, v119, v125, vcc
	ds_write_b32 v17, v119 offset:1024
	s_cmp_lt_u32 s26, 3
	s_cbranch_scc1 .Lpr_gu_done
	v_add_f32_e32 v52, v52, v53
	v_add_f32_e32 v54, v54, v55
	v_add_f32_e32 v52, v52, v54
	v_add_f32_e32 v56, v56, v57
	v_add_f32_e32 v58, v58, v59
	v_add_f32_e32 v56, v56, v58
	v_add_f32_e32 v60, v60, v61
	v_add_f32_e32 v62, v62, v63
	v_add_f32_e32 v60, v60, v62
	v_add_f32_e32 v64, v64, v65
	v_add_f32_e32 v66, v66, v67
	v_add_f32_e32 v64, v64, v66
	v_add_f32_e32 v52, v52, v56
	v_add_f32_e32 v60, v60, v64
	v_add_f32_e32 v120, v52, v60
	v_fmamk_f32 v120, v120, 0x3a800000, v230
	v_mul_f32_e32 v126, 0x4b800000, v120
	v_cmp_gt_f32_e32 vcc, s35, v120
	s_nop 1
	v_cndmask_b32_e32 v120, v120, v126, vcc
	v_rsq_f32_e32 v120, v120
	s_nop 0
	v_mul_f32_e32 v126, 0x45800000, v120
	v_cndmask_b32_e32 v120, v120, v126, vcc
	ds_write_b32 v17, v120 offset:2048
	s_cmp_lt_u32 s26, 4
	s_cbranch_scc1 .Lpr_gu_done
	v_add_f32_e32 v68, v68, v69
	v_add_f32_e32 v70, v70, v71
	v_add_f32_e32 v68, v68, v70
	v_add_f32_e32 v72, v72, v73
	v_add_f32_e32 v74, v74, v75
	v_add_f32_e32 v72, v72, v74
	v_add_f32_e32 v76, v76, v77
	v_add_f32_e32 v78, v78, v79
	v_add_f32_e32 v76, v76, v78
	v_add_f32_e32 v80, v80, v81
	v_add_f32_e32 v82, v82, v83
	v_add_f32_e32 v80, v80, v82
	v_add_f32_e32 v68, v68, v72
	v_add_f32_e32 v76, v76, v80
	v_add_f32_e32 v121, v68, v76
	v_fmamk_f32 v121, v121, 0x3a800000, v230
	v_mul_f32_e32 v127, 0x4b800000, v121
	v_cmp_gt_f32_e32 vcc, s35, v121
	s_nop 1
	v_cndmask_b32_e32 v121, v121, v127, vcc
	v_rsq_f32_e32 v121, v121
	s_nop 0
	v_mul_f32_e32 v127, 0x45800000, v121
	v_cndmask_b32_e32 v121, v121, v127, vcc
	ds_write_b32 v17, v121 offset:3072
	s_cmp_lt_u32 s26, 5
	s_cbranch_scc1 .Lpr_gu_done
	v_add_f32_e32 v84, v84, v85
	v_add_f32_e32 v86, v86, v87
	v_add_f32_e32 v84, v84, v86
	v_add_f32_e32 v88, v88, v89
	v_add_f32_e32 v90, v90, v91
	v_add_f32_e32 v88, v88, v90
	v_add_f32_e32 v92, v92, v93
	v_add_f32_e32 v94, v94, v95
	v_add_f32_e32 v92, v92, v94
	v_add_f32_e32 v96, v96, v97
	v_add_f32_e32 v98, v98, v99
	v_add_f32_e32 v96, v96, v98
	v_add_f32_e32 v84, v84, v88
	v_add_f32_e32 v92, v92, v96
	v_add_f32_e32 v122, v84, v92
	v_fmamk_f32 v122, v122, 0x3a800000, v230
	v_mul_f32_e32 v128, 0x4b800000, v122
	v_cmp_gt_f32_e32 vcc, s35, v122
	s_nop 1
	v_cndmask_b32_e32 v122, v122, v128, vcc
	v_rsq_f32_e32 v122, v122
	s_nop 0
	v_mul_f32_e32 v128, 0x45800000, v122
	v_cndmask_b32_e32 v122, v122, v128, vcc
	ds_write_b32 v17, v122 offset:4096
	s_cmp_lt_u32 s26, 6
	s_cbranch_scc1 .Lpr_gu_done
	v_add_f32_e32 v100, v100, v101
	v_add_f32_e32 v102, v102, v103
	v_add_f32_e32 v100, v100, v102
	v_add_f32_e32 v104, v104, v105
	v_add_f32_e32 v106, v106, v107
	v_add_f32_e32 v104, v104, v106
	v_add_f32_e32 v108, v108, v109
	v_add_f32_e32 v110, v110, v111
	v_add_f32_e32 v108, v108, v110
	v_add_f32_e32 v112, v112, v113
	v_add_f32_e32 v114, v114, v115
	v_add_f32_e32 v112, v112, v114
	v_add_f32_e32 v100, v100, v104
	v_add_f32_e32 v108, v108, v112
	v_add_f32_e32 v123, v100, v108
	v_fmamk_f32 v123, v123, 0x3a800000, v230
	v_mul_f32_e32 v129, 0x4b800000, v123
	v_cmp_gt_f32_e32 vcc, s35, v123
	s_nop 1
	v_cndmask_b32_e32 v123, v123, v129, vcc
	v_rsq_f32_e32 v123, v123
	s_nop 0
	v_mul_f32_e32 v129, 0x45800000, v123
	v_cndmask_b32_e32 v123, v123, v129, vcc
	ds_write_b32 v17, v123 offset:5120
.Lpr_gu_done:
	s_or_b64 exec, exec, s[12:13]
.LBB0_204:
	s_ashr_i32 s6, s16, 8
	s_cmp_eq_u32 s6, 1
	s_cselect_b64 s[0:1], -1, 0
	s_cmp_lg_u32 s6, 1
	s_waitcnt vmcnt(0) lgkmcnt(0)
	s_barrier
	s_cbranch_scc1 .LBB0_206
	s_barrier
